# P1 k_rope epilogue de-serialised: 16 cos/sin loads issued up front into unused accumulator VGPRs (on top of P2 epilogue hoists)
# baseline (speedup 1.0000x reference)
.LBB0_222:
	s_cmp_gt_u32 s16, 14
	s_cbranch_scc0 .LBB0_231
	s_andn2_b64 vcc, exec, s[42:43]
	s_cbranch_vccnz .LBB0_230
	v_ashrrev_i32_e32 v161, 31, v160
	v_lshlrev_b64 v[128:129], 7, v[160:161]
	v_lshl_add_u64 v[130:131], v[148:149], 0, v[128:129]
	v_lshl_add_u64 v[132:133], v[150:151], 0, v[128:129]
	s_mov_b32 s101, 0
	s_movk_i32 s100, 0x1000
	v_lshl_add_u64 v[218:219], v[130:131], 0, s[100:101]
	v_lshl_add_u64 v[220:221], v[132:133], 0, s[100:101]
	s_movk_i32 s100, 0x4000
	v_lshl_add_u64 v[222:223], v[130:131], 0, s[100:101]
	v_lshl_add_u64 v[224:225], v[132:133], 0, s[100:101]
	s_movk_i32 s100, 0x5000
	v_lshl_add_u64 v[226:227], v[130:131], 0, s[100:101]
	v_lshl_add_u64 v[228:229], v[132:133], 0, s[100:101]
	global_load_dwordx4 v[0:3], v[130:131], off offset:2048
	global_load_dwordx4 v[4:7], v[132:133], off offset:2048
	global_load_dwordx4 v[8:11], v[218:219], off
	global_load_dwordx4 v[16:19], v[220:221], off
	global_load_dwordx4 v[24:27], v[218:219], off offset:2048
	global_load_dwordx4 v[32:35], v[220:221], off offset:2048
	global_load_dwordx4 v[40:43], v[222:223], off
	global_load_dwordx4 v[48:51], v[224:225], off
	global_load_dwordx4 v[64:67], v[222:223], off offset:2048
	global_load_dwordx4 v[68:71], v[224:225], off offset:2048
	global_load_dwordx4 v[72:75], v[226:227], off
	global_load_dwordx4 v[80:83], v[228:229], off
	global_load_dwordx4 v[88:91], v[226:227], off offset:2048
	global_load_dwordx4 v[96:99], v[228:229], off offset:2048
	global_load_dwordx4 v[128:131], v[130:131], off
	s_nop 0
	global_load_dwordx4 v[132:135], v[132:133], off
	v_mov_b64_e32 v[162:163], s[28:29]
	v_lshlrev_b32_e32 v144, 1, v146
	v_mad_i64_i32 v[166:167], s[10:11], v160, s94, v[162:163]
	v_or_b32_e32 v164, 16, v160
	v_lshl_add_u64 v[166:167], v[166:167], 0, v[144:145]
	v_ashrrev_i32_e32 v165, 31, v164
	v_lshl_add_u64 v[176:177], v[166:167], 0, s[46:47]
	v_add_co_u32_e32 v166, vcc, s88, v166
	v_lshlrev_b64 v[168:169], 7, v[164:165]
	s_nop 0
	v_addc_co_u32_e32 v167, vcc, 0, v167, vcc
	v_lshl_add_u64 v[178:179], v[148:149], 0, v[168:169]
	v_lshl_add_u64 v[168:169], v[150:151], 0, v[168:169]
	v_mul_f32_e32 v188, v103, v103
	v_mul_f32_e32 v191, v85, v85
	v_mul_f32_e32 v192, v87, v87
	v_mul_f32_e32 v195, v61, v61
	v_mul_f32_e32 v196, v63, v63
	v_mul_f32_e32 v197, v53, v53
	v_fmac_f32_e32 v188, v102, v102
	v_fmac_f32_e32 v191, v84, v84
	v_fmac_f32_e32 v192, v86, v86
	v_fmac_f32_e32 v195, v60, v60
	v_fmac_f32_e32 v196, v62, v62
	v_fmac_f32_e32 v197, v52, v52
	v_mul_f32_e32 v189, v77, v77
	v_mul_f32_e32 v193, v57, v57
	v_mul_f32_e32 v190, v79, v79
	v_mul_f32_e32 v194, v59, v59
	v_fmac_f32_e32 v189, v76, v76
	v_fmac_f32_e32 v193, v56, v56
	v_fmac_f32_e32 v190, v78, v78
	v_fmac_f32_e32 v194, v58, v58
	s_waitcnt vmcnt(0)
	v_mov_b32_e32 v180, v128
	v_mov_b32_e32 v183, v128
	v_mov_b32_e32 v128, v133
	v_mov_b32_e32 v184, v130
	v_mov_b32_e32 v187, v130
	v_mov_b32_e32 v130, v135
	v_mov_b32_e32 v181, v132
	v_mov_b32_e32 v182, v132
	v_mov_b32_e32 v132, v129
	v_mov_b32_e32 v185, v134
	v_mov_b32_e32 v186, v134
	v_mov_b32_e32 v134, v131
	v_pk_mul_f32 v[128:129], v[126:127], v[128:129]
	v_pk_mul_f32 v[130:131], v[122:123], v[130:131]
	v_pk_mul_f32 v[180:181], v[124:125], v[180:181]
	v_pk_mul_f32 v[182:183], v[124:125], v[182:183]
	v_pk_mul_f32 v[132:133], v[126:127], v[132:133]
	v_pk_mul_f32 v[184:185], v[120:121], v[184:185]
	v_pk_mul_f32 v[186:187], v[120:121], v[186:187]
	v_pk_mul_f32 v[134:135], v[122:123], v[134:135]
	v_add_f32_e32 v129, v129, v128
	v_add_f32_e32 v131, v131, v130
	v_sub_f32_e32 v161, v180, v181
	v_add_f32_e32 v165, v183, v182
	v_sub_f32_e32 v132, v132, v133
	v_sub_f32_e32 v133, v184, v185
	v_add_f32_e32 v180, v187, v186
	v_sub_f32_e32 v134, v134, v135
	v_cvt_pk_bf16_f32 v128, v161, v165
	v_cvt_pk_bf16_f32 v129, v132, v129
	v_cvt_pk_bf16_f32 v130, v133, v180
	v_cvt_pk_bf16_f32 v131, v134, v131
	global_store_dwordx4 v[166:167], v[128:131], off offset:256
	global_store_dwordx4 v[176:177], v[128:131], off offset:384
	global_store_dwordx4 v[176:177], v[128:131], off offset:768
	global_store_dwordx4 v[176:177], v[128:131], off offset:1152
	global_store_dwordx4 v[176:177], v[128:131], off offset:1536
	global_store_dwordx4 v[176:177], v[128:131], off offset:1920
	global_store_dwordx4 v[176:177], v[128:131], off offset:2304
	global_store_dwordx4 v[176:177], v[128:131], off offset:2688
	s_nop 1
	v_mov_b64_e32 v[128:129], v[0:1]
	v_mov_b64_e32 v[130:131], v[2:3]
	v_mov_b64_e32 v[166:167], v[4:5]
	v_mov_b64_e32 v[168:169], v[6:7]
	v_mad_i64_i32 v[134:135], s[10:11], v164, s94, v[162:163]
	v_or_b32_e32 v132, 32, v160
	v_lshl_add_u64 v[134:135], v[134:135], 0, v[144:145]
	v_ashrrev_i32_e32 v133, 31, v132
	v_lshl_add_u64 v[176:177], v[134:135], 0, s[46:47]
	v_add_co_u32_e32 v134, vcc, s88, v134
	v_lshlrev_b64 v[164:165], 7, v[132:133]
	s_nop 0
	v_addc_co_u32_e32 v135, vcc, 0, v135, vcc
	v_lshl_add_u64 v[178:179], v[148:149], 0, v[164:165]
	v_lshl_add_u64 v[164:165], v[150:151], 0, v[164:165]
	v_mov_b32_e32 v180, v128
	v_mov_b32_e32 v183, v128
	v_mov_b32_e32 v128, v167
	v_mov_b32_e32 v184, v130
	v_mov_b32_e32 v187, v130
	v_mov_b32_e32 v130, v169
	v_mov_b32_e32 v181, v166
	v_mov_b32_e32 v182, v166
	v_mov_b32_e32 v166, v129
	v_mov_b32_e32 v185, v168
	v_mov_b32_e32 v186, v168
	v_mov_b32_e32 v168, v131
	v_pk_mul_f32 v[128:129], v[118:119], v[128:129]
	v_pk_mul_f32 v[130:131], v[110:111], v[130:131]
	v_pk_mul_f32 v[180:181], v[116:117], v[180:181]
	v_pk_mul_f32 v[182:183], v[116:117], v[182:183]
	v_pk_mul_f32 v[166:167], v[118:119], v[166:167]
	v_pk_mul_f32 v[184:185], v[108:109], v[184:185]
	v_pk_mul_f32 v[186:187], v[108:109], v[186:187]
	v_pk_mul_f32 v[168:169], v[110:111], v[168:169]
	v_add_f32_e32 v129, v129, v128
	v_add_f32_e32 v131, v131, v130
	v_sub_f32_e32 v133, v180, v181
	v_add_f32_e32 v161, v183, v182
	v_sub_f32_e32 v166, v166, v167
	v_sub_f32_e32 v167, v184, v185
	v_add_f32_e32 v180, v187, v186
	v_sub_f32_e32 v168, v168, v169
	v_cvt_pk_bf16_f32 v128, v133, v161
	v_cvt_pk_bf16_f32 v129, v166, v129
	v_cvt_pk_bf16_f32 v130, v167, v180
	v_cvt_pk_bf16_f32 v131, v168, v131
	global_store_dwordx4 v[134:135], v[128:131], off offset:256
	global_store_dwordx4 v[176:177], v[128:131], off offset:384
	global_store_dwordx4 v[176:177], v[128:131], off offset:768
	global_store_dwordx4 v[176:177], v[128:131], off offset:1152
	global_store_dwordx4 v[176:177], v[128:131], off offset:1536
	global_store_dwordx4 v[176:177], v[128:131], off offset:1920
	global_store_dwordx4 v[176:177], v[128:131], off offset:2304
	global_store_dwordx4 v[176:177], v[128:131], off offset:2688
	s_nop 1
	v_mov_b64_e32 v[128:129], v[8:9]
	v_mov_b64_e32 v[130:131], v[10:11]
	v_mov_b64_e32 v[164:165], v[16:17]
	v_mov_b64_e32 v[166:167], v[18:19]
	v_mad_i64_i32 v[132:133], s[10:11], v132, s94, v[162:163]
	v_or_b32_e32 v134, 48, v160
	v_lshl_add_u64 v[132:133], v[132:133], 0, v[144:145]
	v_ashrrev_i32_e32 v135, 31, v134
	v_lshl_add_u64 v[176:177], v[132:133], 0, s[46:47]
	v_add_co_u32_e32 v132, vcc, s88, v132
	v_lshlrev_b64 v[168:169], 7, v[134:135]
	s_nop 0
	v_addc_co_u32_e32 v133, vcc, 0, v133, vcc
	v_lshl_add_u64 v[178:179], v[148:149], 0, v[168:169]
	v_lshl_add_u64 v[168:169], v[150:151], 0, v[168:169]
	v_mov_b32_e32 v180, v128
	v_mov_b32_e32 v183, v128
	v_mov_b32_e32 v128, v165
	v_mov_b32_e32 v184, v130
	v_mov_b32_e32 v187, v130
	v_mov_b32_e32 v130, v167
	v_mov_b32_e32 v181, v164
	v_mov_b32_e32 v182, v164
	v_mov_b32_e32 v164, v129
	v_mov_b32_e32 v185, v166
	v_mov_b32_e32 v186, v166
	v_mov_b32_e32 v166, v131
	v_pk_mul_f32 v[128:129], v[102:103], v[128:129]
	v_pk_mul_f32 v[130:131], v[94:95], v[130:131]
	v_pk_mul_f32 v[180:181], v[100:101], v[180:181]
	v_pk_mul_f32 v[182:183], v[100:101], v[182:183]
	v_pk_mul_f32 v[164:165], v[102:103], v[164:165]
	v_pk_mul_f32 v[184:185], v[92:93], v[184:185]
	v_pk_mul_f32 v[186:187], v[92:93], v[186:187]
	v_pk_mul_f32 v[166:167], v[94:95], v[166:167]
	v_add_f32_e32 v129, v129, v128
	v_add_f32_e32 v131, v131, v130
	v_sub_f32_e32 v135, v180, v181
	v_add_f32_e32 v161, v183, v182
	v_sub_f32_e32 v164, v164, v165
	v_sub_f32_e32 v165, v184, v185
	v_add_f32_e32 v180, v187, v186
	v_sub_f32_e32 v166, v166, v167
	v_cvt_pk_bf16_f32 v128, v135, v161
	v_cvt_pk_bf16_f32 v129, v164, v129
	v_cvt_pk_bf16_f32 v130, v165, v180
	v_cvt_pk_bf16_f32 v131, v166, v131
	global_store_dwordx4 v[132:133], v[128:131], off offset:256
	global_store_dwordx4 v[176:177], v[128:131], off offset:384
	global_store_dwordx4 v[176:177], v[128:131], off offset:768
	global_store_dwordx4 v[176:177], v[128:131], off offset:1152
	global_store_dwordx4 v[176:177], v[128:131], off offset:1536
	global_store_dwordx4 v[176:177], v[128:131], off offset:1920
	global_store_dwordx4 v[176:177], v[128:131], off offset:2304
	global_store_dwordx4 v[176:177], v[128:131], off offset:2688
	s_nop 1
	v_mov_b64_e32 v[128:129], v[24:25]
	v_mov_b64_e32 v[130:131], v[26:27]
	v_mov_b64_e32 v[164:165], v[32:33]
	v_mov_b64_e32 v[166:167], v[34:35]
	v_mad_i64_i32 v[134:135], s[10:11], v134, s94, v[162:163]
	v_add_u32_e32 v132, 0x80, v160
	v_lshl_add_u64 v[134:135], v[134:135], 0, v[144:145]
	v_ashrrev_i32_e32 v133, 31, v132
	v_lshl_add_u64 v[176:177], v[134:135], 0, s[46:47]
	v_add_co_u32_e32 v134, vcc, s88, v134
	v_lshlrev_b64 v[168:169], 7, v[132:133]
	s_nop 0
	v_addc_co_u32_e32 v135, vcc, 0, v135, vcc
	v_lshl_add_u64 v[178:179], v[148:149], 0, v[168:169]
	v_lshl_add_u64 v[168:169], v[150:151], 0, v[168:169]
	v_mov_b32_e32 v180, v128
	v_mov_b32_e32 v183, v128
	v_mov_b32_e32 v128, v165
	v_mov_b32_e32 v184, v130
	v_mov_b32_e32 v187, v130
	v_mov_b32_e32 v130, v167
	v_mov_b32_e32 v181, v164
	v_mov_b32_e32 v182, v164
	v_mov_b32_e32 v164, v129
	v_mov_b32_e32 v185, v166
	v_mov_b32_e32 v186, v166
	v_mov_b32_e32 v166, v131
	v_pk_mul_f32 v[128:129], v[86:87], v[128:129]
	v_pk_mul_f32 v[130:131], v[78:79], v[130:131]
	v_pk_mul_f32 v[180:181], v[84:85], v[180:181]
	v_pk_mul_f32 v[182:183], v[84:85], v[182:183]
	v_pk_mul_f32 v[164:165], v[86:87], v[164:165]
	v_pk_mul_f32 v[184:185], v[76:77], v[184:185]
	v_pk_mul_f32 v[186:187], v[76:77], v[186:187]
	v_pk_mul_f32 v[166:167], v[78:79], v[166:167]
	v_add_f32_e32 v129, v129, v128
	v_add_f32_e32 v131, v131, v130
	v_sub_f32_e32 v133, v180, v181
	v_add_f32_e32 v161, v183, v182
	v_sub_f32_e32 v164, v164, v165
	v_sub_f32_e32 v165, v184, v185
	v_add_f32_e32 v180, v187, v186
	v_sub_f32_e32 v166, v166, v167
	v_cvt_pk_bf16_f32 v128, v133, v161
	v_cvt_pk_bf16_f32 v129, v164, v129
	v_cvt_pk_bf16_f32 v130, v165, v180
	v_cvt_pk_bf16_f32 v131, v166, v131
	global_store_dwordx4 v[134:135], v[128:131], off offset:256
	global_store_dwordx4 v[176:177], v[128:131], off offset:384
	global_store_dwordx4 v[176:177], v[128:131], off offset:768
	global_store_dwordx4 v[176:177], v[128:131], off offset:1152
	global_store_dwordx4 v[176:177], v[128:131], off offset:1536
	global_store_dwordx4 v[176:177], v[128:131], off offset:1920
	global_store_dwordx4 v[176:177], v[128:131], off offset:2304
	global_store_dwordx4 v[176:177], v[128:131], off offset:2688
	s_nop 1
	v_mov_b64_e32 v[128:129], v[40:41]
	v_mov_b64_e32 v[130:131], v[42:43]
	v_mov_b64_e32 v[176:177], v[48:49]
	v_mov_b64_e32 v[178:179], v[50:51]
	v_mad_i64_i32 v[132:133], s[10:11], v132, s94, v[162:163]
	v_add_u32_e32 v166, 0x90, v160
	v_lshl_add_u64 v[132:133], v[132:133], 0, v[144:145]
	v_ashrrev_i32_e32 v167, 31, v166
	v_lshl_add_u64 v[164:165], v[132:133], 0, s[46:47]
	v_add_co_u32_e32 v132, vcc, s88, v132
	v_lshlrev_b64 v[134:135], 7, v[166:167]
	s_nop 0
	v_addc_co_u32_e32 v133, vcc, 0, v133, vcc
	v_lshl_add_u64 v[168:169], v[148:149], 0, v[134:135]
	v_lshl_add_u64 v[134:135], v[150:151], 0, v[134:135]
	v_mad_i64_i32 v[198:199], s[10:11], v166, s94, v[162:163]
	v_lshl_add_u64 v[198:199], v[198:199], 0, v[144:145]
	v_lshl_add_u64 v[202:203], v[198:199], 0, s[46:47]
	v_add_co_u32_e32 v198, vcc, s88, v198
	v_mov_b32_e32 v180, v128
	v_mov_b32_e32 v183, v128
	v_mov_b32_e32 v128, v177
	v_mov_b32_e32 v184, v130
	v_mov_b32_e32 v187, v130
	v_mov_b32_e32 v130, v179
	v_mov_b32_e32 v181, v176
	v_mov_b32_e32 v182, v176
	v_mov_b32_e32 v176, v129
	v_mov_b32_e32 v185, v178
	v_mov_b32_e32 v186, v178
	v_mov_b32_e32 v178, v131
	v_pk_mul_f32 v[128:129], v[62:63], v[128:129]
	v_pk_mul_f32 v[130:131], v[58:59], v[130:131]
	v_pk_mul_f32 v[180:181], v[60:61], v[180:181]
	v_pk_mul_f32 v[182:183], v[60:61], v[182:183]
	v_pk_mul_f32 v[176:177], v[62:63], v[176:177]
	v_pk_mul_f32 v[184:185], v[56:57], v[184:185]
	v_pk_mul_f32 v[186:187], v[56:57], v[186:187]
	v_pk_mul_f32 v[178:179], v[58:59], v[178:179]
	v_add_f32_e32 v129, v129, v128
	v_add_f32_e32 v131, v131, v130
	v_sub_f32_e32 v161, v180, v181
	v_add_f32_e32 v167, v183, v182
	v_sub_f32_e32 v176, v176, v177
	v_sub_f32_e32 v177, v184, v185
	v_add_f32_e32 v180, v187, v186
	v_sub_f32_e32 v178, v178, v179
	v_cvt_pk_bf16_f32 v128, v161, v167
	v_cvt_pk_bf16_f32 v129, v176, v129
	v_cvt_pk_bf16_f32 v130, v177, v180
	v_cvt_pk_bf16_f32 v131, v178, v131
	global_store_dwordx4 v[132:133], v[128:131], off offset:256
	global_store_dwordx4 v[164:165], v[128:131], off offset:384
	global_store_dwordx4 v[164:165], v[128:131], off offset:768
	global_store_dwordx4 v[164:165], v[128:131], off offset:1152
	global_store_dwordx4 v[164:165], v[128:131], off offset:1536
	global_store_dwordx4 v[164:165], v[128:131], off offset:1920
	global_store_dwordx4 v[164:165], v[128:131], off offset:2304
	global_store_dwordx4 v[164:165], v[128:131], off offset:2688
	s_nop 1
	v_mov_b64_e32 v[128:129], v[64:65]
	v_mov_b64_e32 v[130:131], v[66:67]
	v_mov_b64_e32 v[132:133], v[68:69]
	v_mov_b64_e32 v[134:135], v[70:71]
	v_add_u32_e32 v164, 0xa0, v160
	v_ashrrev_i32_e32 v165, 31, v164
	v_lshlrev_b64 v[200:201], 7, v[164:165]
	v_addc_co_u32_e32 v199, vcc, 0, v199, vcc
	v_lshl_add_u64 v[206:207], v[148:149], 0, v[200:201]
	v_lshl_add_u64 v[200:201], v[150:151], 0, v[200:201]
	v_and_b32_e32 v182, 64, v174
	v_add_u32_e32 v168, 0xb0, v160
	v_xor_b32_e32 v176, 16, v174
	v_xor_b32_e32 v177, 32, v174
	v_mul_f32_e32 v178, v125, v125
	v_mul_f32_e32 v179, v127, v127
	v_mul_f32_e32 v187, v101, v101
	v_fmac_f32_e32 v178, v124, v124
	v_fmac_f32_e32 v179, v126, v126
	v_fmac_f32_e32 v187, v100, v100
	v_add_f32_e32 v216, v178, v179
	v_add_f32_e32 v187, v187, v188
	v_add_f32_e32 v188, v191, v192
	v_add_f32_e32 v191, v195, v196
	v_mul_f32_e32 v183, v117, v117
	v_mul_f32_e32 v184, v119, v119
	v_fmac_f32_e32 v183, v116, v116
	v_fmac_f32_e32 v184, v118, v118
	v_add_f32_e32 v184, v183, v184
	v_mul_f32_e32 v161, v121, v121
	v_mul_f32_e32 v180, v109, v109
	v_mul_f32_e32 v167, v123, v123
	v_mul_f32_e32 v181, v111, v111
	v_mul_f32_e32 v185, v93, v93
	v_fmac_f32_e32 v161, v120, v120
	v_fmac_f32_e32 v180, v108, v108
	v_mul_f32_e32 v186, v95, v95
	v_fmac_f32_e32 v167, v122, v122
	v_fmac_f32_e32 v181, v110, v110
	v_fmac_f32_e32 v185, v92, v92
	v_add_f32_e32 v161, v216, v161
	v_fmac_f32_e32 v186, v94, v94
	v_add_f32_e32 v161, v167, v161
	v_mov_b32_e32 v208, v128
	v_mov_b32_e32 v211, v128
	v_mov_b32_e32 v128, v133
	v_mov_b32_e32 v212, v130
	v_mov_b32_e32 v215, v130
	v_mov_b32_e32 v130, v135
	v_mov_b32_e32 v209, v132
	v_mov_b32_e32 v210, v132
	v_mov_b32_e32 v132, v129
	v_mov_b32_e32 v213, v134
	v_mov_b32_e32 v214, v134
	v_mov_b32_e32 v134, v131
	v_pk_mul_f32 v[128:129], v[54:55], v[128:129]
	v_pk_mul_f32 v[130:131], v[46:47], v[130:131]
	v_pk_mul_f32 v[208:209], v[52:53], v[208:209]
	v_pk_mul_f32 v[210:211], v[52:53], v[210:211]
	v_pk_mul_f32 v[132:133], v[54:55], v[132:133]
	v_pk_mul_f32 v[212:213], v[44:45], v[212:213]
	v_pk_mul_f32 v[214:215], v[44:45], v[214:215]
	v_pk_mul_f32 v[134:135], v[46:47], v[134:135]
	v_add_f32_e32 v129, v129, v128
	v_add_f32_e32 v131, v131, v130
	v_sub_f32_e32 v165, v208, v209
	v_add_f32_e32 v166, v211, v210
	v_sub_f32_e32 v132, v132, v133
	v_sub_f32_e32 v133, v212, v213
	v_add_f32_e32 v169, v215, v214
	v_sub_f32_e32 v134, v134, v135
	v_cvt_pk_bf16_f32 v128, v165, v166
	v_cvt_pk_bf16_f32 v129, v132, v129
	v_cvt_pk_bf16_f32 v130, v133, v169
	v_cvt_pk_bf16_f32 v131, v134, v131
	global_store_dwordx4 v[198:199], v[128:131], off offset:256
	global_store_dwordx4 v[202:203], v[128:131], off offset:384
	global_store_dwordx4 v[202:203], v[128:131], off offset:768
	global_store_dwordx4 v[202:203], v[128:131], off offset:1152
	global_store_dwordx4 v[202:203], v[128:131], off offset:1536
	global_store_dwordx4 v[202:203], v[128:131], off offset:1920
	global_store_dwordx4 v[202:203], v[128:131], off offset:2304
	global_store_dwordx4 v[202:203], v[128:131], off offset:2688
	s_nop 1
	v_mov_b64_e32 v[128:129], v[72:73]
	v_mov_b64_e32 v[130:131], v[74:75]
	v_mov_b64_e32 v[132:133], v[80:81]
	v_mov_b64_e32 v[134:135], v[82:83]
	v_mad_i64_i32 v[198:199], s[10:11], v164, s94, v[162:163]
	v_add_u32_e32 v164, 64, v182
	v_mad_i64_i32 v[162:163], s[10:11], v168, s94, v[162:163]
	v_cmp_lt_i32_e32 vcc, v176, v164
	v_xor_b32_e32 v212, 1, v174
	v_lshl_add_u64 v[198:199], v[198:199], 0, v[144:145]
	v_lshl_add_u64 v[162:163], v[162:163], 0, v[144:145]
	v_cndmask_b32_e32 v144, v174, v176, vcc
	v_cmp_lt_i32_e32 vcc, v177, v164
	v_mul_f32_e32 v200, v37, v37
	v_mul_f32_e32 v201, v39, v39
	v_mul_f32_e32 v202, v21, v21
	v_mul_f32_e32 v203, v23, v23
	v_cndmask_b32_e32 v215, v174, v177, vcc
	v_cmp_lt_i32_e32 vcc, v212, v164
	v_mul_f32_e32 v166, v55, v55
	v_fmac_f32_e32 v200, v36, v36
	v_fmac_f32_e32 v201, v38, v38
	v_fmac_f32_e32 v202, v20, v20
	v_fmac_f32_e32 v203, v22, v22
	v_cndmask_b32_e32 v212, v174, v212, vcc
	v_add_co_u32_e32 v178, vcc, s88, v198
	v_fmac_f32_e32 v166, v54, v54
	v_add_f32_e32 v192, v200, v201
	v_add_f32_e32 v195, v202, v203
	v_lshl_add_u64 v[176:177], v[198:199], 0, s[46:47]
	v_addc_co_u32_e32 v179, vcc, 0, v199, vcc
	v_add_f32_e32 v166, v197, v166
	v_ashrrev_i32_e32 v169, 31, v168
	v_lshlrev_b64 v[168:169], 7, v[168:169]
	v_lshl_add_u64 v[182:183], v[148:149], 0, v[168:169]
	v_lshl_add_u64 v[168:169], v[150:151], 0, v[168:169]
	v_mul_f32_e32 v206, v45, v45
	v_mul_f32_e32 v208, v29, v29
	v_mul_f32_e32 v210, v13, v13
	v_mul_f32_e32 v207, v47, v47
	v_mul_f32_e32 v209, v31, v31
	v_mul_f32_e32 v211, v15, v15
	v_fmac_f32_e32 v206, v44, v44
	v_fmac_f32_e32 v208, v28, v28
	v_fmac_f32_e32 v210, v12, v12
	v_fmac_f32_e32 v207, v46, v46
	v_fmac_f32_e32 v209, v30, v30
	v_fmac_f32_e32 v211, v14, v14
	v_lshlrev_b32_e32 v144, 2, v144
	v_add_f32_e32 v166, v166, v206
	v_add_f32_e32 v166, v207, v166
	v_xor_b32_e32 v213, 2, v174
	v_cmp_lt_i32_e32 vcc, v213, v164
	v_xor_b32_e32 v214, 4, v174
	v_xor_b32_e32 v165, 8, v174
	v_mov_b32_e32 v196, v128
	v_mov_b32_e32 v199, v128
	v_mov_b32_e32 v128, v133
	v_mov_b32_e32 v200, v130
	v_mov_b32_e32 v203, v130
	v_mov_b32_e32 v130, v135
	v_mov_b32_e32 v197, v132
	v_mov_b32_e32 v198, v132
	v_mov_b32_e32 v132, v129
	v_mov_b32_e32 v201, v134
	v_mov_b32_e32 v202, v134
	v_mov_b32_e32 v134, v131
	v_pk_mul_f32 v[128:129], v[38:39], v[128:129]
	v_pk_mul_f32 v[130:131], v[30:31], v[130:131]
	v_pk_mul_f32 v[196:197], v[36:37], v[196:197]
	v_pk_mul_f32 v[198:199], v[36:37], v[198:199]
	v_pk_mul_f32 v[132:133], v[38:39], v[132:133]
	v_pk_mul_f32 v[200:201], v[28:29], v[200:201]
	v_pk_mul_f32 v[202:203], v[28:29], v[202:203]
	v_pk_mul_f32 v[134:135], v[30:31], v[134:135]
	v_add_f32_e32 v129, v129, v128
	v_add_f32_e32 v131, v131, v130
	v_sub_f32_e32 v196, v196, v197
	v_add_f32_e32 v197, v199, v198
	v_sub_f32_e32 v132, v132, v133
	v_sub_f32_e32 v133, v200, v201
	v_add_f32_e32 v198, v203, v202
	v_sub_f32_e32 v134, v134, v135
	v_cvt_pk_bf16_f32 v128, v196, v197
	v_cvt_pk_bf16_f32 v129, v132, v129
	v_cvt_pk_bf16_f32 v130, v133, v198
	v_cvt_pk_bf16_f32 v131, v134, v131
	global_store_dwordx4 v[178:179], v[128:131], off offset:256
	global_store_dwordx4 v[176:177], v[128:131], off offset:384
	global_store_dwordx4 v[176:177], v[128:131], off offset:768
	global_store_dwordx4 v[176:177], v[128:131], off offset:1152
	global_store_dwordx4 v[176:177], v[128:131], off offset:1536
	global_store_dwordx4 v[176:177], v[128:131], off offset:1920
	global_store_dwordx4 v[176:177], v[128:131], off offset:2304
	global_store_dwordx4 v[176:177], v[128:131], off offset:2688
	s_nop 1
	v_mov_b64_e32 v[128:129], v[88:89]
	v_mov_b64_e32 v[130:131], v[90:91]
	v_mov_b64_e32 v[132:133], v[96:97]
	v_mov_b64_e32 v[134:135], v[98:99]
	v_add_f32_e32 v169, v184, v180
	v_add_f32_e32 v176, v187, v185
	v_add_f32_e32 v177, v188, v189
	v_add_f32_e32 v178, v191, v193
	v_add_f32_e32 v179, v192, v208
	v_add_f32_e32 v180, v195, v210
	v_add_f32_e32 v167, v181, v169
	v_add_f32_e32 v169, v186, v176
	v_add_f32_e32 v176, v190, v177
	v_add_f32_e32 v177, v194, v178
	v_add_f32_e32 v178, v209, v179
	v_add_f32_e32 v179, v211, v180
	ds_bpermute_b32 v180, v144, v161
	ds_bpermute_b32 v181, v144, v167
	ds_bpermute_b32 v183, v144, v169
	ds_bpermute_b32 v184, v144, v176
	ds_bpermute_b32 v185, v144, v177
	ds_bpermute_b32 v186, v144, v166
	ds_bpermute_b32 v187, v144, v178
	ds_bpermute_b32 v144, v144, v179
	v_lshlrev_b32_e32 v168, 2, v215
	s_waitcnt lgkmcnt(7)
	v_add_f32_e32 v161, v161, v180
	s_waitcnt lgkmcnt(6)
	v_add_f32_e32 v167, v167, v181
	s_waitcnt lgkmcnt(5)
	v_add_f32_e32 v169, v169, v183
	s_waitcnt lgkmcnt(4)
	v_add_f32_e32 v176, v176, v184
	s_waitcnt lgkmcnt(0)
	v_add_f32_e32 v144, v179, v144
	ds_bpermute_b32 v179, v168, v161
	ds_bpermute_b32 v180, v168, v167
	v_add_f32_e32 v177, v177, v185
	v_add_f32_e32 v166, v166, v186
	ds_bpermute_b32 v181, v168, v169
	ds_bpermute_b32 v183, v168, v176
	v_add_f32_e32 v178, v178, v187
	ds_bpermute_b32 v184, v168, v177
	ds_bpermute_b32 v185, v168, v166
	ds_bpermute_b32 v186, v168, v178
	ds_bpermute_b32 v168, v168, v144
	s_waitcnt lgkmcnt(7)
	v_add_f32_e32 v161, v161, v179
	s_waitcnt lgkmcnt(6)
	v_add_f32_e32 v167, v167, v180
	s_waitcnt lgkmcnt(5)
	v_add_f32_e32 v169, v169, v181
	s_waitcnt lgkmcnt(4)
	v_add_f32_e32 v176, v176, v183
	v_max3_f32 v161, v161, 0, v167
	s_waitcnt lgkmcnt(3)
	v_add_f32_e32 v177, v177, v184
	s_waitcnt lgkmcnt(2)
	v_add_f32_e32 v166, v166, v185
	v_max3_f32 v161, v161, v169, v176
	s_waitcnt lgkmcnt(1)
	v_add_f32_e32 v178, v178, v186
	s_waitcnt lgkmcnt(0)
	v_add_f32_e32 v144, v144, v168
	v_max3_f32 v161, v161, v177, v166
	v_lshlrev_b32_e32 v182, 2, v212
	v_max3_f32 v144, v161, v178, v144
	ds_bpermute_b32 v161, v182, v144
	v_cndmask_b32_e32 v166, v174, v213, vcc
	v_lshlrev_b32_e32 v166, 2, v166
	v_cmp_lt_i32_e32 vcc, v214, v164
	s_waitcnt lgkmcnt(0)
	v_max_f32_e32 v161, v161, v161
	v_max_f32_e32 v144, v144, v161
	ds_bpermute_b32 v161, v166, v144
	v_cndmask_b32_e32 v167, v174, v214, vcc
	v_lshlrev_b32_e32 v167, 2, v167
	v_cmp_lt_i32_e32 vcc, v165, v164
	s_waitcnt lgkmcnt(0)
	v_max_f32_e32 v161, v161, v161
	v_max_f32_e32 v144, v144, v161
	ds_bpermute_b32 v161, v167, v144
	v_cndmask_b32_e32 v166, v174, v165, vcc
	v_lshlrev_b32_e32 v166, 2, v166
	v_lshl_add_u64 v[164:165], v[162:163], 0, s[46:47]
	v_add_co_u32_e32 v162, vcc, s88, v162
	s_waitcnt lgkmcnt(0)
	v_max_f32_e32 v161, v161, v161
	v_max_f32_e32 v144, v144, v161
	ds_bpermute_b32 v161, v166, v144
	v_addc_co_u32_e32 v163, vcc, 0, v163, vcc
	v_mov_b32_e32 v166, v128
	v_mov_b32_e32 v169, v128
	v_mov_b32_e32 v128, v133
	v_mov_b32_e32 v176, v130
	v_mov_b32_e32 v179, v130
	v_mov_b32_e32 v130, v135
	v_mov_b32_e32 v167, v132
	v_mov_b32_e32 v168, v132
	v_mov_b32_e32 v132, v129
	v_mov_b32_e32 v177, v134
	v_mov_b32_e32 v178, v134
	v_mov_b32_e32 v134, v131
	v_pk_mul_f32 v[128:129], v[22:23], v[128:129]
	v_pk_mul_f32 v[130:131], v[14:15], v[130:131]
	v_pk_mul_f32 v[166:167], v[20:21], v[166:167]
	v_pk_mul_f32 v[168:169], v[20:21], v[168:169]
	v_pk_mul_f32 v[132:133], v[22:23], v[132:133]
	v_pk_mul_f32 v[176:177], v[12:13], v[176:177]
	v_pk_mul_f32 v[178:179], v[12:13], v[178:179]
	v_pk_mul_f32 v[134:135], v[14:15], v[134:135]
	v_add_f32_e32 v129, v129, v128
	v_add_f32_e32 v131, v131, v130
	v_sub_f32_e32 v166, v166, v167
	v_add_f32_e32 v167, v169, v168
	v_sub_f32_e32 v132, v132, v133
	v_sub_f32_e32 v133, v176, v177
	v_add_f32_e32 v168, v179, v178
	v_sub_f32_e32 v134, v134, v135
	v_cvt_pk_bf16_f32 v128, v166, v167
	v_cvt_pk_bf16_f32 v129, v132, v129
	v_cvt_pk_bf16_f32 v130, v133, v168
	v_cvt_pk_bf16_f32 v131, v134, v131
	global_store_dwordx4 v[162:163], v[128:131], off offset:256
	global_store_dwordx4 v[164:165], v[128:131], off offset:384
	global_store_dwordx4 v[164:165], v[128:131], off offset:768
	global_store_dwordx4 v[164:165], v[128:131], off offset:1152
	global_store_dwordx4 v[164:165], v[128:131], off offset:1536
	global_store_dwordx4 v[164:165], v[128:131], off offset:1920
	global_store_dwordx4 v[164:165], v[128:131], off offset:2304
	global_store_dwordx4 v[164:165], v[128:131], off offset:2688
	s_and_saveexec_b64 s[74:75], s[4:5]
	s_cbranch_execz .LBB0_229
	s_waitcnt lgkmcnt(0)
	v_max_f32_e32 v128, v161, v161
	v_max_f32_e32 v129, v144, v144
	s_mov_b64 s[76:77], exec
	v_max_f32_e32 v128, v129, v128
	s_mov_b32 s10, 0
